# code placement: 32-byte pad after the kernel's first scalar loads shifts all loop bodies by 32 bytes
# baseline (speedup 1.0000x reference)
_Z10fwd_kernel6Params:
	s_load_dwordx8 s[12:19], s[0:1], 0x1a0
	s_load_dwordx8 s[4:11], s[0:1], 0x180
	s_nop 0
	s_nop 0
	s_nop 0
	s_nop 0
	s_nop 0
	s_nop 0
	s_nop 0
	s_nop 0
	v_and_b32_e32 v220, 0x3ff, v0
	v_writelane_b32 v252, s2, 0
	s_waitcnt lgkmcnt(0)
	v_writelane_b32 v252, s4, 1
	s_nop 1
	v_writelane_b32 v252, s5, 2
	v_writelane_b32 v252, s6, 3
	v_writelane_b32 v252, s7, 4
	v_writelane_b32 v252, s8, 5
	v_writelane_b32 v252, s9, 6
	v_writelane_b32 v252, s10, 7
	v_writelane_b32 v252, s11, 8
	v_cmp_eq_u32_e64 s[4:5], 0, v220
	s_mov_b64 s[2:3], exec
	s_nop 0
	v_writelane_b32 v252, s4, 9
	s_nop 1
	v_writelane_b32 v252, s5, 10
	s_and_b64 s[4:5], s[2:3], s[4:5]
	s_mov_b64 exec, s[4:5]
	v_mov_b32_e32 v2, 0
	v_mov_b32_e32 v3, v2
	v_mov_b32_e32 v4, v2
	v_mov_b32_e32 v5, v2
	ds_write_b128 v2, v[2:5]
	s_or_b64 exec, exec, s[2:3]
	s_waitcnt lgkmcnt(0)
	s_barrier
	s_getreg_b32 s2, hwreg(HW_REG_XCC_ID, 0, 4)
	s_and_b32 s6, s2, 15
	s_mov_b64 s[2:3], exec
	v_readlane_b32 s4, v252, 9
	v_readlane_b32 s5, v252, 10
	s_and_b64 s[4:5], s[2:3], s[4:5]
	s_mov_b64 exec, s[4:5]
	s_cbranch_execz .LBB0_5
	s_mov_b64 s[4:5], exec
	v_mbcnt_lo_u32_b32 v1, s4, 0
	v_mbcnt_hi_u32_b32 v1, s5, v1
	v_cmp_eq_u32_e32 vcc, 0, v1
	s_and_b64 s[8:9], exec, vcc
	s_mov_b64 exec, s[8:9]
	s_cbranch_execz .LBB0_5
	s_lshl_b32 s7, s6, 8
	s_bcnt1_i32_b64 s4, s[4:5]
	v_mov_b32_e32 v1, s7
	v_mov_b32_e32 v2, s4
	global_atomic_add v1, v2, s[14:15] offset:1280
